# GDN scan: state/W LDS reads issued right after the step barrier, ahead of the next-chunk global-load block
# baseline (speedup 1.0000x reference)
; DI void gdn_scan_item(const P& p, int item, unsigned char* smem) {
;     ...
;     auto loadr = [&](GdnRegs& R, int c) {
;         if (c >= 36) return;
;         u32x4* rr = R.r;
; #pragma unroll
;         for (int k = 0; k < 2; ++k) {
;             const int e = tid + 512 * k, r = e >> 4, ch = e & 15; const size_t off = ((size_t)seq * PT + 64 * c + r) * 128 + 8 * ch;
;             rr[k] = *(const u32x4*)(W + off); rr[2 + k] = *(const u32x4*)(QI + off); rr[4 + k] = *(const u32x4*)(KO + off);
;         }
;         { const int r = tid >> 3, ch = tid & 7; rr[6] = *(const u32x4*)(AT + (((size_t)seq * 36 + c) * 64 + r) * 64 + 8 * ch); }
;         if (tid < 256) { const int r = tid >> 2, ch = tid & 3; rr[7] = __builtin_nontemporal_load((const u32x4*)(U + ((size_t)seq * PT + 64 * c + r) * 128 + 32 * cq + 8 * ch)); }
;     };
;     auto storel = [&](const GdnRegs& R, int buf) {
;         const u32x4* rr = R.r;
;         bf16_t* sW = (bf16_t*)(smem + buf * BUFB); bf16_t* sQI = sW + 64 * 136; bf16_t* sKO = sQI + 64 * 136; bf16_t* sAT = sKO + 64 * 136; bf16_t* sU = sAT + 64 * 72;
; #pragma unroll
;         for (int k = 0; k < 2; ++k) {
;             const int e = tid + 512 * k, r = e >> 4, ch = e & 15; const int off = r * 136 + 8 * ch;
;             *(u32x4*)(sW + off) = rr[k]; *(u32x4*)(sQI + off) = rr[2 + k]; *(u32x4*)(sKO + off) = rr[4 + k];
;         }
;         { const int r = tid >> 3, ch = tid & 7; *(u32x4*)(sAT + r * 72 + 8 * ch) = rr[6]; }
;         if (tid < 256) { const int r = tid >> 2, ch = tid & 3; *(u32x4*)(sU + r * 40 + 8 * ch) = rr[7]; }
;     };
;     u32x4* sBS = (u32x4*)(smem + 2 * BUFB + 5120 + 256);
;     f32x4 st[2];
;     st[0] = (f32x4){0.f, 0.f, 0.f, 0.f}; st[1] = (f32x4){0.f, 0.f, 0.f, 0.f};
;     sBS[(nt * 4 + mt) * 64 + lane] = (u32x4){0u, 0u, 0u, 0u};
;     if (tid < 36) sdec[tid] = DC[seq * 36 + tid];
;     const int sgn = dir ? -1 : 1;
;     auto step = [&](GdnRegs& R, int c) {
;         storel(R, c & 1);
;         __syncthreads();
;         loadr(R, c + 3);
;         const bf16_t* sW = (const bf16_t*)(smem + (c & 1) * BUFB); const bf16_t* sQI = sW + 64 * 136; const bf16_t* sKO = sQI + 64 * 136; const bf16_t* sAT = sKO + 64 * 136; const bf16_t* sU = sAT + 64 * 72;
;         const float dec = sdec[c];
;         bf16x8 Bs[4];
; #pragma unroll
.LBB0_501:
	s_add_i32 s26, s27, 3
	s_bitcmp1_b32 s26, 0
	s_cselect_b32 s4, 0x10400, 0
	s_add_i32 s28, s57, s4
	v_lshlrev_b32_e32 v198, 1, v118
	v_lshl_add_u32 v190, v120, 1, s28
	v_lshl_add_u32 v192, v122, 1, s28
	v_add3_u32 v194, s28, v119, v116
	v_add3_u32 v191, s28, v161, v198
	s_waitcnt vmcnt(20)
	ds_write_b128 v190, v[0:3]
	s_waitcnt vmcnt(19)
	ds_write_b128 v190, v[4:7] offset:17408
	s_waitcnt vmcnt(18)
	ds_write_b128 v190, v[8:11] offset:34816
	s_waitcnt vmcnt(17)
	ds_write_b128 v192, v[12:15]
	s_waitcnt vmcnt(16)
	ds_write_b128 v192, v[16:19] offset:17408
	s_waitcnt vmcnt(15)
	ds_write_b128 v192, v[24:27] offset:34816
	s_waitcnt vmcnt(14)
	ds_write_b128 v194, v[36:39] offset:52224
	s_and_saveexec_b64 s[40:41], s[0:1]
	ds_write_b128 v191, v[20:23] offset:61440
	s_or_b64 exec, exec, s[40:41]
	s_cmp_gt_u32 s26, 32
	v_lshl_add_u64 v[154:155], v[148:149], 0, s[44:45]
	v_lshl_add_u64 v[152:153], v[146:147], 0, s[44:45]
	v_lshl_add_u64 v[150:151], v[142:143], 0, s[44:45]
	s_waitcnt lgkmcnt(0)
	s_barrier
	ds_read_b128 v[112:115], v117
	ds_read_b128 v[200:203], v117 offset:1024
	ds_read_b128 v[204:207], v117 offset:2048
	ds_read_b128 v[208:211], v117 offset:3072
	v_lshl_add_u32 v134, v121, 1, s28
	v_mov_b32_e32 v104, s21
	ds_read_b32 v132, v104
	v_add_u32_e32 v188, v134, v162
	ds_read2_b64 v[224:227], v188 offset1:4
	ds_read2_b64 v[228:231], v188 offset0:8 offset1:12
	ds_read2_b64 v[232:235], v188 offset0:16 offset1:20
	ds_read2_b64 v[236:239], v188 offset0:24 offset1:28
	v_add_u32_e32 v134, v134, v158
	s_cbranch_scc1 .LBB0_507
	v_add_co_u32_e32 v0, vcc, 0x13f58000, v154
	s_nop 1
	v_addc_co_u32_e32 v1, vcc, 0, v155, vcc
	v_add_co_u32_e32 v4, vcc, 0x15158000, v154
	s_nop 1
	v_addc_co_u32_e32 v5, vcc, 0, v155, vcc
	v_add_co_u32_e32 v8, vcc, 0x16358000, v154
	global_load_dwordx4 v[0:3], v[0:1], off
	s_nop 0
	global_load_dwordx4 v[4:7], v[4:5], off
	v_addc_co_u32_e32 v9, vcc, 0, v155, vcc
	v_add_co_u32_e32 v12, vcc, 0x13f58000, v152
	global_load_dwordx4 v[8:11], v[8:9], off
	s_nop 0
	v_addc_co_u32_e32 v13, vcc, 0, v153, vcc
	v_add_co_u32_e32 v16, vcc, 0x15158000, v152
	s_nop 1
	v_addc_co_u32_e32 v17, vcc, 0, v153, vcc
	v_add_co_u32_e32 v24, vcc, 0x16358000, v152
	global_load_dwordx4 v[12:15], v[12:13], off
	s_nop 0
	global_load_dwordx4 v[16:19], v[16:17], off
	v_addc_co_u32_e32 v25, vcc, 0, v153, vcc
	v_add_co_u32_e32 v36, vcc, 0x17552000, v150
	global_load_dwordx4 v[24:27], v[24:25], off
	s_nop 0
	v_addc_co_u32_e32 v37, vcc, 0, v151, vcc
	global_load_dwordx4 v[36:39], v[36:37], off
	s_and_saveexec_b64 s[40:41], s[0:1]
	s_cbranch_execz .LBB0_506
	v_lshl_add_u64 v[20:21], v[144:145], 0, s[44:45]
	v_add_co_u32_e32 v20, vcc, 0x12d58000, v20
	s_nop 1
	v_addc_co_u32_e32 v21, vcc, 0, v21, vcc
	global_load_dwordx4 v[20:23], v[20:21], off nt

; DI float lo16(unsigned u) { return __uint_as_float(u << 16); }
; DI float hi16(unsigned u) { return __uint_as_float(u & 0xFFFF0000u); }
; DI bf16x8 tr2(const bf16_t* p0, const bf16_t* p1) { s16x4 a = trread(p0), b = trread(p1); return __builtin_shufflevector(a, b, 0, 1, 2, 3, 4, 5, 6, 7); }
; DI f32x4 mfma16(bf16x8 a, bf16x8 b, f32x4 c) { return __builtin_amdgcn_mfma_f32_16x16x32_bf16(a, b, c, 0, 0, 0); }
; DI void gdn_scan_item(const P& p, int item, unsigned char* smem) {
;     ...
;         {
;             f32x4 acc = (f32x4){0.f, 0.f, 0.f, 0.f};
; #pragma unroll
;             for (int ks = 0; ks < 4; ++ks) { const bf16_t* r0 = sW + (16 * mt + l15) * 136 + 32 * ks + 4 * g; acc = mfma16(Bs[ks], ld4x2(r0, r0 + 16), acc); }
;             {
;                 const u32x2 uu = *(const u32x2*)(sU + (16 * mt + l15) * 40 + 16 * nt + 4 * g);
;                 u32x2 vv; vv.x = pk2(lo16(uu.x) - acc[0], hi16(uu.x) - acc[1]); vv.y = pk2(lo16(uu.y) - acc[2], hi16(uu.y) - acc[3]);
;                 *(u32x2*)(sVN + (16 * mt + l15) * 40 + 16 * nt + 4 * g) = vv;
;             }
;         }
;         __syncthreads();
;         bf16x8 Bv[2];
; #pragma unroll
;         for (int k2 = 0; k2 < 2; ++k2) Bv[k2] = tr2(sVN + (32 * k2 + 8 * g + q4) * 40 + 16 * nt + 4 * p4, sVN + (32 * k2 + 8 * g + 4 + q4) * 40 + 16 * nt + 4 * p4);
;         {
;             f32x4 acc = (f32x4){0.f, 0.f, 0.f, 0.f};
; #pragma unroll
;             for (int ks = 0; ks < 4; ++ks) { const bf16_t* r0 = sQI + (16 * mt + l15) * 136 + 32 * ks + 4 * g; acc = mfma16(Bs[ks], ld4x2(r0, r0 + 16), acc); }
; #pragma unroll
;             for (int k2 = 0; k2 < 2; ++k2) acc = mfma16(Bv[k2], ld8(sAT + (16 * mt + l15) * 72 + 32 * k2 + 8 * g), acc);
;             bf16_t* ob = OG + (size_t)prow(b, dir, 64 * c) * 512 + 128 * h + 32 * cq;
;             u32x2 ov; ov.x = pk2(acc[0], acc[1]); ov.y = pk2(acc[2], acc[3]);
;             *(u32x2*)(ob + sgn * ((16 * mt + l15) * 512) + 16 * nt + 4 * g) = ov;
;         }
.LBB0_507:
	s_waitcnt lgkmcnt(3)
	v_mfma_f32_16x16x32_bf16 v[104:107], v[112:115], v[224:227], 0
	v_add3_u32 v195, v134, v163, v162
	ds_read_b64 v[240:241], v195 offset:61440
	v_add_u32_e32 v189, 0x4000, v188
	v_add_u32_e32 v134, v134, v159
	s_waitcnt lgkmcnt(3)
	v_mfma_f32_16x16x32_bf16 v[104:107], v[200:203], v[228:231], v[104:107]
	v_lshlrev_b32_e32 v199, 1, v124
	v_add3_u32 v196, v134, v160, v199
	s_waitcnt lgkmcnt(2)
	v_mfma_f32_16x16x32_bf16 v[104:107], v[204:207], v[232:235], v[104:107]
	s_mov_b64 s[42:43], -1
	s_cmp_gt_u32 s26, 3
	s_waitcnt lgkmcnt(1)
	v_mfma_f32_16x16x32_bf16 v[104:107], v[208:211], v[236:239], v[104:107]
	s_waitcnt lgkmcnt(0)
	v_lshlrev_b32_e32 v110, 16, v240
	v_and_b32_e32 v108, 0xffff0000, v240
	s_nop 3
	s_nop 0
	v_sub_f32_e32 v104, v110, v104
	v_sub_f32_e32 v105, v108, v105
	v_cvt_pk_bf16_f32 v104, v104, v105
	v_lshlrev_b32_e32 v105, 16, v241
	v_sub_f32_e32 v105, v105, v106
	v_and_b32_e32 v106, 0xffff0000, v241
	v_sub_f32_e32 v106, v106, v107
	v_cvt_pk_bf16_f32 v105, v105, v106
	ds_write_b64 v123, v[104:105]
	s_waitcnt lgkmcnt(0)
	s_barrier
	ds_read_b64_tr_b16 v[108:109], v164
	ds_read_b64_tr_b16 v[110:111], v165
	ds_read_b64_tr_b16 v[104:105], v183
	ds_read_b64_tr_b16 v[106:107], v184
	ds_read2_b64 v[224:227], v189 offset0:128 offset1:132
	ds_read2_b64 v[228:231], v189 offset0:136 offset1:140
	ds_read2_b64 v[232:235], v189 offset0:144 offset1:148
	ds_read2_b64 v[236:239], v189 offset0:152 offset1:156
	ds_read_b128 v[240:243], v196 offset:52224
	ds_read_b128 v[244:247], v196 offset:52288
	s_waitcnt lgkmcnt(5)
	v_mfma_f32_16x16x32_bf16 v[112:115], v[112:115], v[224:227], 0
	s_waitcnt lgkmcnt(4)
	v_mfma_f32_16x16x32_bf16 v[112:115], v[200:203], v[228:231], v[112:115]
	s_waitcnt lgkmcnt(3)
	v_mfma_f32_16x16x32_bf16 v[112:115], v[204:207], v[232:235], v[112:115]
	s_waitcnt lgkmcnt(2)
	v_mfma_f32_16x16x32_bf16 v[112:115], v[208:211], v[236:239], v[112:115]
	s_waitcnt lgkmcnt(1)
	v_mfma_f32_16x16x32_bf16 v[112:115], v[108:111], v[240:243], v[112:115]
	s_waitcnt lgkmcnt(0)
	v_mfma_f32_16x16x32_bf16 v[112:115], v[104:107], v[244:247], v[112:115]
	s_cbranch_scc0 .LBB0_509
	s_add_i32 s6, s22, 0xfffffe80
	s_add_i32 s7, s24, 0x80
	s_and_b64 s[4:5], s[38:39], exec
	s_cselect_b32 s4, s6, s7
	s_add_i32 s40, s4, s2
	s_mov_b64 s[42:43], 0

; DI bf16x8 tr2(const bf16_t* p0, const bf16_t* p1) { s16x4 a = trread(p0), b = trread(p1); return __builtin_shufflevector(a, b, 0, 1, 2, 3, 4, 5, 6, 7); }
; DI void gdn_scan_item(const P& p, int item, unsigned char* smem) {
;     ...
;     auto storel = [&](const GdnRegs& R, int buf) {
;         const u32x4* rr = R.r;
;         bf16_t* sW = (bf16_t*)(smem + buf * BUFB); bf16_t* sQI = sW + 64 * 136; bf16_t* sKO = sQI + 64 * 136; bf16_t* sAT = sKO + 64 * 136; bf16_t* sU = sAT + 64 * 72;
; #pragma unroll
;         for (int k = 0; k < 2; ++k) {
;             const int e = tid + 512 * k, r = e >> 4, ch = e & 15; const int off = r * 136 + 8 * ch;
;             *(u32x4*)(sW + off) = rr[k]; *(u32x4*)(sQI + off) = rr[2 + k]; *(u32x4*)(sKO + off) = rr[4 + k];
;         }
;         { const int r = tid >> 3, ch = tid & 7; *(u32x4*)(sAT + r * 72 + 8 * ch) = rr[6]; }
;         if (tid < 256) { const int r = tid >> 2, ch = tid & 3; *(u32x4*)(sU + r * 40 + 8 * ch) = rr[7]; }
;     };
;     u32x4* sBS = (u32x4*)(smem + 2 * BUFB + 5120 + 256);
;     f32x4 st[2];
;     st[0] = (f32x4){0.f, 0.f, 0.f, 0.f}; st[1] = (f32x4){0.f, 0.f, 0.f, 0.f};
;     sBS[(nt * 4 + mt) * 64 + lane] = (u32x4){0u, 0u, 0u, 0u};
;     if (tid < 36) sdec[tid] = DC[seq * 36 + tid];
;     const int sgn = dir ? -1 : 1;
;     auto step = [&](GdnRegs& R, int c) {
;         storel(R, c & 1);
;         __syncthreads();
;         loadr(R, c + 3);
;         const bf16_t* sW = (const bf16_t*)(smem + (c & 1) * BUFB); const bf16_t* sQI = sW + 64 * 136; const bf16_t* sKO = sQI + 64 * 136; const bf16_t* sAT = sKO + 64 * 136; const bf16_t* sU = sAT + 64 * 72;
;         const float dec = sdec[c];
;         bf16x8 Bs[4];
; #pragma unroll
;         for (int ks = 0; ks < 4; ++ks) Bs[ks] = __builtin_bit_cast(bf16x8, sBS[(nt * 4 + ks) * 64 + lane]);
;     ...
; #pragma unroll
;         for (int j = 0; j < 2; ++j) {
;             const int dt = 2 * mt + j;
;             st[j] *= dec;
; #pragma unroll
;             for (int k2 = 0; k2 < 2; ++k2) {
;                 const bf16x8 ak = tr2(sKO + (32 * k2 + 8 * g + q4) * 136 + 16 * dt + 4 * p4, sKO + (32 * k2 + 8 * g + 4 + q4) * 136 + 16 * dt + 4 * p4);
;                 st[j] = mfma16(ak, Bv[k2], st[j]);
;             }
;         }
;         sBS[(nt * 4 + mt) * 64 + lane] = __builtin_bit_cast(u32x4, packacc(st[0], st[1]));
;     };
.LBB0_511:
	v_lshl_add_u32 v134, v125, 1, s28
	v_lshlrev_b32_e32 v197, 1, v157
	v_add3_u32 v187, v134, v185, v197
	ds_read_b64_tr_b16 v[226:227], v187 offset:35904
	ds_read_b64_tr_b16 v[224:225], v187 offset:34816
	ds_read_b64_tr_b16 v[230:231], v187 offset:44608
	ds_read_b64_tr_b16 v[234:235], v187 offset:35936
	ds_read_b64_tr_b16 v[232:233], v187 offset:34848
	ds_read_b64_tr_b16 v[238:239], v187 offset:44640
	v_add3_u32 v193, v134, v186, v197
	ds_read_b64_tr_b16 v[228:229], v193 offset:34816
	ds_read_b64_tr_b16 v[236:237], v193 offset:34848
	v_pk_mul_f32 v[98:99], v[98:99], v[132:133] op_sel_hi:[1,0]
	v_pk_mul_f32 v[96:97], v[96:97], v[132:133] op_sel_hi:[1,0]
	v_pk_mul_f32 v[102:103], v[102:103], v[132:133] op_sel_hi:[1,0]
	v_pk_mul_f32 v[100:101], v[100:101], v[132:133] op_sel_hi:[1,0]
	s_waitcnt lgkmcnt(6)
	v_mfma_f32_16x16x32_bf16 v[96:99], v[224:227], v[108:111], v[96:99]
	s_ashr_i32 s41, s40, 31
	s_lshl_b64 s[4:5], s[40:41], 10
	s_waitcnt lgkmcnt(3)
	v_mfma_f32_16x16x32_bf16 v[100:103], v[232:235], v[108:111], v[100:103]
	s_bitcmp1_b32 s27, 0
	v_lshl_add_u64 v[108:109], v[126:127], 0, s[4:5]
	s_cselect_b32 s4, 0x10400, 0
	s_waitcnt lgkmcnt(1)
	v_mfma_f32_16x16x32_bf16 v[96:99], v[228:231], v[104:107], v[96:99]
	s_add_i32 s27, s57, s4
	v_cvt_pk_bf16_f32 v112, v112, v113
	v_cvt_pk_bf16_f32 v113, v114, v115
	s_waitcnt lgkmcnt(0)
	v_mfma_f32_16x16x32_bf16 v[100:103], v[236:239], v[104:107], v[100:103]
	global_store_dwordx2 v[108:109], v[112:113], off
	s_nop 1
	v_cvt_pk_bf16_f32 v104, v96, v97
	v_cvt_pk_bf16_f32 v105, v98, v99
	s_nop 2
	v_cvt_pk_bf16_f32 v106, v100, v101
	v_cvt_pk_bf16_f32 v107, v102, v103
	ds_write_b128 v156, v[104:107]
	v_lshl_add_u32 v104, v120, 1, s27
	s_waitcnt vmcnt(14)
	ds_write_b128 v104, v[28:31]
	s_waitcnt vmcnt(13)
	ds_write_b128 v104, v[32:35] offset:17408
	s_waitcnt vmcnt(12)
	ds_write_b128 v104, v[40:43] offset:34816
	v_lshl_add_u32 v104, v122, 1, s27
	s_waitcnt vmcnt(11)
	ds_write_b128 v104, v[48:51]
	s_waitcnt vmcnt(10)
	ds_write_b128 v104, v[52:55] offset:17408
	s_waitcnt vmcnt(9)
	ds_write_b128 v104, v[64:67] offset:34816
	v_add3_u32 v104, s27, v119, v116
	s_waitcnt vmcnt(3)
	ds_write_b128 v104, v[72:75] offset:52224
	s_waitcnt lgkmcnt(0)
	s_and_saveexec_b64 s[40:41], s[0:1]
	v_add3_u32 v104, s27, v161, v198
	ds_write_b128 v104, v[44:47] offset:61440
	s_or_b64 exec, exec, s[40:41]
	s_cmp_gt_u32 s26, 31
	v_readlane_b32 s12, v254, 56
	s_waitcnt lgkmcnt(0)
	s_barrier
	ds_read_b128 v[110:113], v117
	ds_read_b128 v[200:203], v117 offset:1024
	ds_read_b128 v[204:207], v117 offset:2048
	ds_read_b128 v[208:211], v117 offset:3072
	v_lshl_add_u32 v109, v121, 1, s27
	v_mov_b32_e32 v104, s21
	ds_read_b32 v108, v104 offset:4
	v_add_u32_e32 v132, v109, v162
	ds_read2_b64 v[224:227], v132 offset1:4
	ds_read2_b64 v[228:231], v132 offset0:8 offset1:12
	ds_read2_b64 v[236:239], v132 offset0:16 offset1:20
	ds_read2_b64 v[240:243], v132 offset0:24 offset1:28
	v_add_u32_e32 v109, v109, v158
	v_readlane_b32 s13, v254, 57
	s_cbranch_scc1 .LBB0_517
	v_add_co_u32_e32 v28, vcc, 0x13f5c000, v154
	s_nop 1
	v_addc_co_u32_e32 v29, vcc, 0, v155, vcc
	v_add_co_u32_e32 v32, vcc, 0x1515c000, v154
	s_nop 1
	v_addc_co_u32_e32 v33, vcc, 0, v155, vcc
	v_add_co_u32_e32 v40, vcc, 0x1635c000, v154
	global_load_dwordx4 v[28:31], v[28:29], off
	s_nop 0
	global_load_dwordx4 v[32:35], v[32:33], off
	v_addc_co_u32_e32 v41, vcc, 0, v155, vcc
	v_add_co_u32_e32 v48, vcc, 0x13f5c000, v152
	global_load_dwordx4 v[40:43], v[40:41], off
	s_nop 0
	v_addc_co_u32_e32 v49, vcc, 0, v153, vcc
	v_add_co_u32_e32 v52, vcc, 0x1515c000, v152
	s_nop 1
	v_addc_co_u32_e32 v53, vcc, 0, v153, vcc
	v_add_co_u32_e32 v64, vcc, 0x1635c000, v152
	global_load_dwordx4 v[48:51], v[48:49], off
	s_nop 0
	global_load_dwordx4 v[52:55], v[52:53], off
	v_addc_co_u32_e32 v65, vcc, 0, v153, vcc
	v_add_co_u32_e32 v72, vcc, 0x17554000, v150
	global_load_dwordx4 v[64:67], v[64:65], off
	s_nop 0
	v_addc_co_u32_e32 v73, vcc, 0, v151, vcc
	global_load_dwordx4 v[72:75], v[72:73], off
	s_and_saveexec_b64 s[40:41], s[0:1]
	s_cbranch_execz .LBB0_516
	v_lshl_add_u64 v[44:45], v[144:145], 0, s[44:45]
	v_add_co_u32_e32 v44, vcc, 0x12d5c000, v44
	s_nop 1
	v_addc_co_u32_e32 v45, vcc, 0, v45, vcc
	global_load_dwordx4 v[44:47], v[44:45], off nt

; DI float lo16(unsigned u) { return __uint_as_float(u << 16); }
; DI void gdn_scan_item(const P& p, int item, unsigned char* smem) {
;     ...
;     auto step = [&](GdnRegs& R, int c) {
;         storel(R, c & 1);
;         __syncthreads();
;         loadr(R, c + 3);
;         const bf16_t* sW = (const bf16_t*)(smem + (c & 1) * BUFB); const bf16_t* sQI = sW + 64 * 136; const bf16_t* sKO = sQI + 64 * 136; const bf16_t* sAT = sKO + 64 * 136; const bf16_t* sU = sAT + 64 * 72;
;         const float dec = sdec[c];
;         bf16x8 Bs[4];
; #pragma unroll
;         for (int ks = 0; ks < 4; ++ks) Bs[ks] = __builtin_bit_cast(bf16x8, sBS[(nt * 4 + ks) * 64 + lane]);
;         {
;             f32x4 acc = (f32x4){0.f, 0.f, 0.f, 0.f};
; #pragma unroll
;             for (int ks = 0; ks < 4; ++ks) { const bf16_t* r0 = sW + (16 * mt + l15) * 136 + 32 * ks + 4 * g; acc = mfma16(Bs[ks], ld4x2(r0, r0 + 16), acc); }
;             {
;                 const u32x2 uu = *(const u32x2*)(sU + (16 * mt + l15) * 40 + 16 * nt + 4 * g);
;                 u32x2 vv; vv.x = pk2(lo16(uu.x) - acc[0], hi16(uu.x) - acc[1]); vv.y = pk2(lo16(uu.y) - acc[2], hi16(uu.y) - acc[3]);
;                 *(u32x2*)(sVN + (16 * mt + l15) * 40 + 16 * nt + 4 * g) = vv;
;             }
;         }
;         __syncthreads();
;         bf16x8 Bv[2];
; #pragma unroll
;         for (int k2 = 0; k2 < 2; ++k2) Bv[k2] = tr2(sVN + (32 * k2 + 8 * g + q4) * 40 + 16 * nt + 4 * p4, sVN + (32 * k2 + 8 * g + 4 + q4) * 40 + 16 * nt + 4 * p4);
;         {
;             f32x4 acc = (f32x4){0.f, 0.f, 0.f, 0.f};
; #pragma unroll
;             for (int ks = 0; ks < 4; ++ks) { const bf16_t* r0 = sQI + (16 * mt + l15) * 136 + 32 * ks + 4 * g; acc = mfma16(Bs[ks], ld4x2(r0, r0 + 16), acc); }
; #pragma unroll
;             for (int k2 = 0; k2 < 2; ++k2) acc = mfma16(Bv[k2], ld8(sAT + (16 * mt + l15) * 72 + 32 * k2 + 8 * g), acc);
;             bf16_t* ob = OG + (size_t)prow(b, dir, 64 * c) * 512 + 128 * h + 32 * cq;
;             u32x2 ov; ov.x = pk2(acc[0], acc[1]); ov.y = pk2(acc[2], acc[3]);
;             *(u32x2*)(ob + sgn * ((16 * mt + l15) * 512) + 16 * nt + 4 * g) = ov;
;         }
; #pragma unroll
;         for (int j = 0; j < 2; ++j) {
;             const int dt = 2 * mt + j;
;             st[j] *= dec;
; #pragma unroll
;             for (int k2 = 0; k2 < 2; ++k2) {
.LBB0_517:
	s_waitcnt lgkmcnt(3)
	v_mfma_f32_16x16x32_bf16 v[104:107], v[110:113], v[224:227], 0
	v_add3_u32 v114, v109, v163, v162
	ds_read_b64 v[232:233], v114 offset:61440
	v_add_u32_e32 v109, v109, v159
	s_waitcnt lgkmcnt(3)
	v_mfma_f32_16x16x32_bf16 v[104:107], v[200:203], v[228:231], v[104:107]
	v_add3_u32 v109, v109, v160, v199
	s_waitcnt lgkmcnt(0)
	v_lshlrev_b32_e32 v134, 16, v232
	v_mfma_f32_16x16x32_bf16 v[104:107], v[204:207], v[236:239], v[104:107]
	v_and_b32_e32 v114, 0xffff0000, v232
	s_sub_i32 s4, s22, 64
	v_mfma_f32_16x16x32_bf16 v[104:107], v[208:211], v[240:243], v[104:107]
	s_add_i32 s5, s22, 0xfffffec0
	s_cmp_lt_u32 s26, 3
	s_movk_i32 s6, 0x8ff
	s_nop 4
	v_sub_f32_e32 v104, v134, v104
	v_sub_f32_e32 v105, v114, v105
	v_cvt_pk_bf16_f32 v104, v104, v105
	v_lshlrev_b32_e32 v105, 16, v233
	v_sub_f32_e32 v105, v105, v106
	v_and_b32_e32 v106, 0xffff0000, v233
	v_sub_f32_e32 v106, v106, v107
	v_cvt_pk_bf16_f32 v105, v105, v106
	v_add_u32_e32 v114, 0x4000, v132
	ds_write_b64 v123, v[104:105]
	s_waitcnt lgkmcnt(0)
	s_barrier
	ds_read_b64_tr_b16 v[224:225], v164
	ds_read_b64_tr_b16 v[226:227], v165
	ds_read_b64_tr_b16 v[228:229], v183
	ds_read_b64_tr_b16 v[230:231], v184
	ds_read2_b64 v[232:235], v114 offset0:128 offset1:132
	ds_read2_b64 v[236:239], v114 offset0:136 offset1:140
	ds_read2_b64 v[240:243], v114 offset0:144 offset1:148
	ds_read2_b64 v[244:247], v114 offset0:152 offset1:156
	ds_read_b128 v[248:251], v109 offset:52224
	s_waitcnt lgkmcnt(4)
	v_mfma_f32_16x16x32_bf16 v[110:113], v[110:113], v[232:235], 0
	ds_read_b128 v[232:235], v109 offset:52288
	s_cselect_b32 s6, 0xff, s6
	s_cselect_b32 s7, s4, s5
	s_waitcnt lgkmcnt(4)
	v_mfma_f32_16x16x32_bf16 v[110:113], v[200:203], v[236:239], v[110:113]
	s_cselect_b32 s8, s3, s2
	s_add_i32 s4, s6, s24
	s_waitcnt lgkmcnt(3)
	v_mfma_f32_16x16x32_bf16 v[110:113], v[204:207], v[240:243], v[110:113]
	s_add_i32 s6, s4, 0xfffff741
	s_and_b64 s[4:5], s[38:39], exec
	s_waitcnt lgkmcnt(2)
	v_mfma_f32_16x16x32_bf16 v[110:113], v[208:211], v[244:247], v[110:113]
	s_cselect_b32 s4, s7, s6
	s_add_i32 s4, s4, s8
	s_waitcnt lgkmcnt(1)
	v_mfma_f32_16x16x32_bf16 v[110:113], v[224:227], v[248:251], v[110:113]
	s_ashr_i32 s5, s4, 31
	s_lshl_b64 s[4:5], s[4:5], 10
	s_waitcnt lgkmcnt(0)
	v_mfma_f32_16x16x32_bf16 v[110:113], v[228:231], v[232:235], v[110:113]
	v_mul_f32_e64 v98, v98, v108
	v_mul_f32_e64 v99, v99, v108
	v_pk_mul_f32 v[96:97], v[96:97], v[108:109] op_sel_hi:[1,0]
	v_lshl_add_u32 v109, v125, 1, s27
	s_nop 3
	v_cvt_pk_bf16_f32 v110, v110, v111
	v_cvt_pk_bf16_f32 v111, v112, v113
	v_lshl_add_u64 v[112:113], v[126:127], 0, s[4:5]
	global_store_dwordx2 v[112:113], v[110:111], off
	v_add3_u32 v114, v109, v185, v197
	ds_read_b64_tr_b16 v[238:239], v114 offset:35904
	ds_read_b64_tr_b16 v[236:237], v114 offset:34816
	ds_read_b64_tr_b16 v[240:241], v114 offset:34848
	ds_read_b64_tr_b16 v[246:247], v114 offset:44608
	ds_read_b64_tr_b16 v[242:243], v114 offset:35936
	ds_read_b64_tr_b16 v[250:251], v114 offset:44640
	s_waitcnt lgkmcnt(4)
	v_mfma_f32_16x16x32_bf16 v[96:99], v[236:239], v[224:227], v[96:99]
	v_add3_u32 v109, v109, v186, v197
	ds_read_b64_tr_b16 v[244:245], v109 offset:34816
	ds_read_b64_tr_b16 v[248:249], v109 offset:34848
	v_pk_mul_f32 v[102:103], v[102:103], v[108:109] op_sel_hi:[1,0]
	v_pk_mul_f32 v[100:101], v[100:101], v[108:109] op_sel_hi:[1,0]
	s_waitcnt lgkmcnt(1)
	v_mfma_f32_16x16x32_bf16 v[96:99], v[244:247], v[228:231], v[96:99]
	v_mfma_f32_16x16x32_bf16 v[100:103], v[240:243], v[224:227], v[100:103]
	s_waitcnt lgkmcnt(0)
	v_mfma_f32_16x16x32_bf16 v[100:103], v[248:251], v[228:231], v[100:103]
	s_nop 3
	s_nop 0
	v_cvt_pk_bf16_f32 v104, v96, v97
	v_cvt_pk_bf16_f32 v105, v98, v99
	s_nop 1
	v_cvt_pk_bf16_f32 v106, v100, v101
	v_cvt_pk_bf16_f32 v107, v102, v103
	ds_write_b128 v156, v[104:107]
	s_waitcnt vmcnt(8)
	ds_write_b128 v190, v[56:59]
	s_waitcnt vmcnt(7)
	ds_write_b128 v190, v[60:63] offset:17408
	s_waitcnt vmcnt(6)
	ds_write_b128 v190, v[68:71] offset:34816
	s_waitcnt vmcnt(5)
	ds_write_b128 v192, v[76:79]
	s_waitcnt vmcnt(4)
	ds_write_b128 v192, v[80:83] offset:17408
	s_waitcnt vmcnt(3)
	ds_write_b128 v192, v[84:87] offset:34816
	s_waitcnt vmcnt(2)
	ds_write_b128 v194, v[92:95] offset:52224
	s_waitcnt lgkmcnt(0)
	s_and_saveexec_b64 s[40:41], s[0:1]
	ds_write_b128 v191, v[88:91] offset:61440
	s_or_b64 exec, exec, s[40:41]
	s_cmp_gt_u32 s26, 30
	s_waitcnt lgkmcnt(0)
	s_barrier
	ds_read_b128 v[112:115], v117
	ds_read_b128 v[248:251], v117 offset:1024
	ds_read_b128 v[198:201], v117 offset:2048
	ds_read_b128 v[202:205], v117 offset:3072
	ds_read2_b64 v[224:227], v188 offset1:4
	ds_read2_b64 v[228:231], v188 offset0:8 offset1:12
	ds_read2_b64 v[232:235], v188 offset0:16 offset1:20
	ds_read2_b64 v[236:239], v188 offset0:24 offset1:28
	ds_read_b64 v[240:241], v195 offset:61440
	v_mov_b32_e32 v104, s21
	ds_read_b32 v132, v104 offset:8
	s_cbranch_scc1 .LBB0_523
	v_add_co_u32_e32 v56, vcc, 0x13f60000, v154
	s_nop 1
	v_addc_co_u32_e32 v57, vcc, 0, v155, vcc
	v_add_co_u32_e32 v60, vcc, 0x15160000, v154
	s_nop 1
	v_addc_co_u32_e32 v61, vcc, 0, v155, vcc
	v_add_co_u32_e32 v68, vcc, 0x16360000, v154
	global_load_dwordx4 v[56:59], v[56:57], off
	s_nop 0
	global_load_dwordx4 v[60:63], v[60:61], off
	v_addc_co_u32_e32 v69, vcc, 0, v155, vcc
	v_add_co_u32_e32 v76, vcc, 0x13f60000, v152
	global_load_dwordx4 v[68:71], v[68:69], off
	s_nop 0
	v_addc_co_u32_e32 v77, vcc, 0, v153, vcc
	v_add_co_u32_e32 v80, vcc, 0x15160000, v152
	s_nop 1
	v_addc_co_u32_e32 v81, vcc, 0, v153, vcc
	v_add_co_u32_e32 v84, vcc, 0x16360000, v152
	global_load_dwordx4 v[76:79], v[76:77], off
	s_nop 0
	global_load_dwordx4 v[80:83], v[80:81], off
	v_addc_co_u32_e32 v85, vcc, 0, v153, vcc
	v_add_co_u32_e32 v92, vcc, 0x17556000, v150
	global_load_dwordx4 v[84:87], v[84:85], off
	s_nop 0
	v_addc_co_u32_e32 v93, vcc, 0, v151, vcc
	global_load_dwordx4 v[92:95], v[92:93], off
	s_and_saveexec_b64 s[40:41], s[0:1]
	s_cbranch_execz .LBB0_522
	v_lshl_add_u64 v[88:89], v[144:145], 0, s[44:45]
	v_add_co_u32_e32 v88, vcc, 0x12d60000, v88
	s_nop 1
	v_addc_co_u32_e32 v89, vcc, 0, v89, vcc
	global_load_dwordx4 v[88:91], v[88:89], off nt

; DI float lo16(unsigned u) { return __uint_as_float(u << 16); }
; DI float hi16(unsigned u) { return __uint_as_float(u & 0xFFFF0000u); }
; DI bf16x8 tr2(const bf16_t* p0, const bf16_t* p1) { s16x4 a = trread(p0), b = trread(p1); return __builtin_shufflevector(a, b, 0, 1, 2, 3, 4, 5, 6, 7); }
; DI f32x4 mfma16(bf16x8 a, bf16x8 b, f32x4 c) { return __builtin_amdgcn_mfma_f32_16x16x32_bf16(a, b, c, 0, 0, 0); }
; DI void gdn_scan_item(const P& p, int item, unsigned char* smem) {
;     ...
;         {
;             f32x4 acc = (f32x4){0.f, 0.f, 0.f, 0.f};
; #pragma unroll
;             for (int ks = 0; ks < 4; ++ks) { const bf16_t* r0 = sW + (16 * mt + l15) * 136 + 32 * ks + 4 * g; acc = mfma16(Bs[ks], ld4x2(r0, r0 + 16), acc); }
;             {
;                 const u32x2 uu = *(const u32x2*)(sU + (16 * mt + l15) * 40 + 16 * nt + 4 * g);
;                 u32x2 vv; vv.x = pk2(lo16(uu.x) - acc[0], hi16(uu.x) - acc[1]); vv.y = pk2(lo16(uu.y) - acc[2], hi16(uu.y) - acc[3]);
;                 *(u32x2*)(sVN + (16 * mt + l15) * 40 + 16 * nt + 4 * g) = vv;
;             }
;         }
;         __syncthreads();
;         bf16x8 Bv[2];
; #pragma unroll
;         for (int k2 = 0; k2 < 2; ++k2) Bv[k2] = tr2(sVN + (32 * k2 + 8 * g + q4) * 40 + 16 * nt + 4 * p4, sVN + (32 * k2 + 8 * g + 4 + q4) * 40 + 16 * nt + 4 * p4);
;         {
;             f32x4 acc = (f32x4){0.f, 0.f, 0.f, 0.f};
; #pragma unroll
;             for (int ks = 0; ks < 4; ++ks) { const bf16_t* r0 = sQI + (16 * mt + l15) * 136 + 32 * ks + 4 * g; acc = mfma16(Bs[ks], ld4x2(r0, r0 + 16), acc); }
; #pragma unroll
;             for (int k2 = 0; k2 < 2; ++k2) acc = mfma16(Bv[k2], ld8(sAT + (16 * mt + l15) * 72 + 32 * k2 + 8 * g), acc);
;             bf16_t* ob = OG + (size_t)prow(b, dir, 64 * c) * 512 + 128 * h + 32 * cq;
;             u32x2 ov; ov.x = pk2(acc[0], acc[1]); ov.y = pk2(acc[2], acc[3]);
;             *(u32x2*)(ob + sgn * ((16 * mt + l15) * 512) + 16 * nt + 4 * g) = ov;
;         }
.LBB0_523:
	s_mov_b64 s[40:41], -1
	s_cmp_gt_u32 s26, 1
	s_waitcnt lgkmcnt(5)
	v_mfma_f32_16x16x32_bf16 v[104:107], v[112:115], v[224:227], 0
	s_waitcnt lgkmcnt(4)
	v_mfma_f32_16x16x32_bf16 v[104:107], v[248:251], v[228:231], v[104:107]
	s_waitcnt lgkmcnt(3)
	v_mfma_f32_16x16x32_bf16 v[104:107], v[198:201], v[232:235], v[104:107]
	s_waitcnt lgkmcnt(2)
	v_mfma_f32_16x16x32_bf16 v[104:107], v[202:205], v[236:239], v[104:107]
	s_waitcnt lgkmcnt(1)
	v_lshlrev_b32_e32 v110, 16, v240
	v_and_b32_e32 v108, 0xffff0000, v240
	s_nop 3
	s_nop 0
	v_sub_f32_e32 v104, v110, v104
	v_sub_f32_e32 v105, v108, v105
	v_cvt_pk_bf16_f32 v104, v104, v105
	v_lshlrev_b32_e32 v105, 16, v241
	v_sub_f32_e32 v105, v105, v106
	v_and_b32_e32 v106, 0xffff0000, v241
	v_sub_f32_e32 v106, v106, v107
	v_cvt_pk_bf16_f32 v105, v105, v106
	ds_write_b64 v123, v[104:105]
	s_waitcnt lgkmcnt(0)
	s_barrier
	ds_read_b64_tr_b16 v[108:109], v164
	ds_read_b64_tr_b16 v[110:111], v165
	ds_read_b64_tr_b16 v[104:105], v183
	ds_read_b64_tr_b16 v[106:107], v184
	ds_read2_b64 v[224:227], v189 offset0:128 offset1:132
	ds_read2_b64 v[228:231], v189 offset0:136 offset1:140
	ds_read2_b64 v[232:235], v189 offset0:144 offset1:148
	ds_read2_b64 v[236:239], v189 offset0:152 offset1:156
	ds_read_b128 v[240:243], v196 offset:52224
	ds_read_b128 v[244:247], v196 offset:52288
	s_waitcnt lgkmcnt(5)
	v_mfma_f32_16x16x32_bf16 v[112:115], v[112:115], v[224:227], 0
	s_waitcnt lgkmcnt(4)
	v_mfma_f32_16x16x32_bf16 v[112:115], v[248:251], v[228:231], v[112:115]
	s_waitcnt lgkmcnt(3)
	v_mfma_f32_16x16x32_bf16 v[112:115], v[198:201], v[232:235], v[112:115]
	s_waitcnt lgkmcnt(2)
	v_mfma_f32_16x16x32_bf16 v[112:115], v[202:205], v[236:239], v[112:115]
	s_waitcnt lgkmcnt(1)
	v_mfma_f32_16x16x32_bf16 v[112:115], v[108:111], v[240:243], v[112:115]
	s_waitcnt lgkmcnt(0)
	v_mfma_f32_16x16x32_bf16 v[112:115], v[104:107], v[244:247], v[112:115]
	s_cbranch_scc0 .LBB0_525
	s_add_i32 s6, s22, 0xffffff00
	s_and_b64 s[4:5], s[38:39], exec
	s_cselect_b32 s4, s6, s24
	s_add_i32 s42, s4, s2
	s_mov_b64 s[40:41], 0
